# EpiResid (down and w_out): second-half residual-row loads issued with the first half's into v[222:253] (one round trip per epilogue); on top of the de-serialisation bundle
# baseline (speedup 1.0000x reference)
.LBB0_438:
	v_lshl_or_b32 v140, s27, 8, v204
	v_lshl_add_u32 v144, s26, 8, v202
	s_lshl_b64 s[26:27], s[28:29], 2
	s_add_u32 s26, s17, s26
	s_addc_u32 s27, s71, s27
	v_ashrrev_i32_e32 v141, 31, v140
	v_lshl_add_u64 v[142:143], v[140:141], 2, s[26:27]
	global_load_dwordx4 v[178:181], v[142:143], off offset:16
	global_load_dwordx4 v[182:185], v[142:143], off
	global_load_dwordx4 v[170:173], v[142:143], off offset:528
	global_load_dwordx4 v[174:177], v[142:143], off offset:512
	v_lshlrev_b64 v[186:187], 1, v[140:141]
	v_ashrrev_i32_e32 v145, 31, v144
	v_lshl_add_u64 v[188:189], s[10:11], 0, v[186:187]
	v_lshlrev_b64 v[190:191], 12, v[144:145]
	s_mov_b64 s[26:27], 0x80000
	s_andn2_b64 vcc, exec, s[4:5]
	v_lshl_add_u64 v[132:133], v[188:189], 0, v[190:191]
	v_lshl_add_u64 v[212:213], v[132:133], 0, s[26:27]
	global_load_dwordx4 v[222:225], v[212:213], off
	global_load_dwordx4 v[226:229], v[212:213], off offset:256
	global_load_dwordx4 v[206:209], v[132:133], off
	global_load_dwordx4 v[156:159], v[132:133], off offset:256
	v_or_b32_e32 v132, 16, v144
	v_ashrrev_i32_e32 v133, 31, v132
	v_lshlrev_b64 v[200:201], 12, v[132:133]
	v_lshl_add_u64 v[132:133], v[188:189], 0, v[200:201]
	v_lshl_add_u64 v[212:213], v[132:133], 0, s[26:27]
	global_load_dwordx4 v[230:233], v[212:213], off
	global_load_dwordx4 v[234:237], v[212:213], off offset:256
	global_load_dwordx4 v[152:155], v[132:133], off
	global_load_dwordx4 v[148:151], v[132:133], off offset:256
	v_or_b32_e32 v132, 32, v144
	v_ashrrev_i32_e32 v133, 31, v132
	v_lshlrev_b64 v[192:193], 12, v[132:133]
	v_lshl_add_u64 v[132:133], v[188:189], 0, v[192:193]
	v_lshl_add_u64 v[212:213], v[132:133], 0, s[26:27]
	global_load_dwordx4 v[238:241], v[212:213], off
	global_load_dwordx4 v[242:245], v[212:213], off offset:256
	global_load_dwordx4 v[140:143], v[132:133], off
	s_nop 0
	global_load_dwordx4 v[132:135], v[132:133], off offset:256
	v_or_b32_e32 v136, 48, v144
	v_ashrrev_i32_e32 v137, 31, v136
	v_lshlrev_b64 v[194:195], 12, v[136:137]
	v_lshl_add_u64 v[136:137], v[188:189], 0, v[194:195]
	v_lshl_add_u64 v[212:213], v[136:137], 0, s[26:27]
	global_load_dwordx4 v[246:249], v[212:213], off
	global_load_dwordx4 v[250:253], v[212:213], off offset:256
	global_load_dwordx4 v[144:147], v[136:137], off
	s_nop 0
	global_load_dwordx4 v[136:139], v[136:137], off offset:256
	s_waitcnt vmcnt(0)
	v_pk_mul_f32 v[170:171], v[170:171], 0.5 op_sel_hi:[1,0]
	v_pk_mul_f32 v[172:173], v[172:173], 0.5 op_sel_hi:[1,0]
	v_pk_mul_f32 v[174:175], v[174:175], 0.5 op_sel_hi:[1,0]
	v_pk_mul_f32 v[176:177], v[176:177], 0.5 op_sel_hi:[1,0]
	v_pk_mul_f32 v[178:179], v[178:179], 0.5 op_sel_hi:[1,0]
	v_pk_mul_f32 v[180:181], v[180:181], 0.5 op_sel_hi:[1,0]
	v_pk_mul_f32 v[182:183], v[182:183], 0.5 op_sel_hi:[1,0]
	v_pk_mul_f32 v[184:185], v[184:185], 0.5 op_sel_hi:[1,0]
	s_waitcnt vmcnt(7)
	v_lshlrev_b32_e32 v210, 16, v206
	v_and_b32_e32 v211, 0xffff0000, v206
	v_lshlrev_b32_e32 v206, 16, v207
	v_and_b32_e32 v207, 0xffff0000, v207
	v_pk_fma_f32 v[130:131], v[130:131], v[184:185], v[206:207]
	v_pk_fma_f32 v[128:129], v[128:129], v[182:183], v[210:211]
	v_lshlrev_b32_e32 v206, 16, v208
	v_and_b32_e32 v207, 0xffff0000, v208
	v_lshlrev_b32_e32 v208, 16, v209
	v_and_b32_e32 v209, 0xffff0000, v209
	v_pk_fma_f32 v[208:209], v[126:127], v[180:181], v[208:209]
	v_pk_fma_f32 v[126:127], v[124:125], v[178:179], v[206:207]
	v_cvt_pk_bf16_f32 v124, v128, v129
	v_lshl_add_u64 v[128:129], s[10:11], 0, v[190:191]
	v_cvt_pk_bf16_f32 v125, v130, v131
	v_cvt_pk_bf16_f32 v126, v126, v127
	v_cvt_pk_bf16_f32 v127, v208, v209
	v_lshl_add_u64 v[128:129], v[128:129], 0, v[186:187]
	global_store_dwordx4 v[128:129], v[124:127], off
	s_waitcnt vmcnt(7)
	s_nop 0
	v_lshlrev_b32_e32 v124, 16, v156
	v_and_b32_e32 v125, 0xffff0000, v156
	v_lshlrev_b32_e32 v126, 16, v157
	v_and_b32_e32 v127, 0xffff0000, v157
	v_pk_fma_f32 v[122:123], v[122:123], v[176:177], v[126:127]
	v_pk_fma_f32 v[120:121], v[120:121], v[174:175], v[124:125]
	v_lshlrev_b32_e32 v124, 16, v158
	v_and_b32_e32 v125, 0xffff0000, v158
	v_lshlrev_b32_e32 v126, 16, v159
	v_and_b32_e32 v127, 0xffff0000, v159
	v_pk_fma_f32 v[126:127], v[118:119], v[172:173], v[126:127]
	v_pk_fma_f32 v[118:119], v[116:117], v[170:171], v[124:125]
	v_cvt_pk_bf16_f32 v116, v120, v121
	v_cvt_pk_bf16_f32 v117, v122, v123
	s_nop 0
	v_cvt_pk_bf16_f32 v118, v118, v119
	v_cvt_pk_bf16_f32 v119, v126, v127
	global_store_dwordx4 v[128:129], v[116:119], off offset:256
	s_waitcnt vmcnt(7)
	s_nop 0
	v_lshlrev_b32_e32 v116, 16, v152
	v_and_b32_e32 v117, 0xffff0000, v152
	v_lshlrev_b32_e32 v118, 16, v153
	v_and_b32_e32 v119, 0xffff0000, v153
	v_pk_fma_f32 v[114:115], v[114:115], v[184:185], v[118:119]
	v_pk_fma_f32 v[112:113], v[112:113], v[182:183], v[116:117]
	v_lshlrev_b32_e32 v116, 16, v154
	v_and_b32_e32 v117, 0xffff0000, v154
	v_lshlrev_b32_e32 v118, 16, v155
	v_and_b32_e32 v119, 0xffff0000, v155
	v_pk_fma_f32 v[118:119], v[110:111], v[180:181], v[118:119]
	v_pk_fma_f32 v[110:111], v[108:109], v[178:179], v[116:117]
	v_cvt_pk_bf16_f32 v108, v112, v113
	v_lshl_add_u64 v[112:113], s[10:11], 0, v[200:201]
	v_cvt_pk_bf16_f32 v109, v114, v115
	v_cvt_pk_bf16_f32 v110, v110, v111
	v_cvt_pk_bf16_f32 v111, v118, v119
	v_lshl_add_u64 v[112:113], v[112:113], 0, v[186:187]
	global_store_dwordx4 v[112:113], v[108:111], off
	s_waitcnt vmcnt(7)
	s_nop 0
	v_lshlrev_b32_e32 v108, 16, v148
	v_and_b32_e32 v109, 0xffff0000, v148
	v_lshlrev_b32_e32 v110, 16, v149
	v_and_b32_e32 v111, 0xffff0000, v149
	v_pk_fma_f32 v[106:107], v[106:107], v[176:177], v[110:111]
	v_pk_fma_f32 v[104:105], v[104:105], v[174:175], v[108:109]
	v_lshlrev_b32_e32 v108, 16, v150
	v_and_b32_e32 v109, 0xffff0000, v150
	v_lshlrev_b32_e32 v110, 16, v151
	v_and_b32_e32 v111, 0xffff0000, v151
	v_pk_fma_f32 v[110:111], v[102:103], v[172:173], v[110:111]
	v_pk_fma_f32 v[102:103], v[100:101], v[170:171], v[108:109]
	v_cvt_pk_bf16_f32 v100, v104, v105
	v_cvt_pk_bf16_f32 v101, v106, v107
	s_nop 0
	v_cvt_pk_bf16_f32 v102, v102, v103
	v_cvt_pk_bf16_f32 v103, v110, v111
	global_store_dwordx4 v[112:113], v[100:103], off offset:256
	s_waitcnt vmcnt(7)
	s_nop 0
	v_lshlrev_b32_e32 v100, 16, v140
	v_and_b32_e32 v101, 0xffff0000, v140
	v_lshlrev_b32_e32 v102, 16, v141
	v_and_b32_e32 v103, 0xffff0000, v141
	v_pk_fma_f32 v[98:99], v[98:99], v[184:185], v[102:103]
	v_pk_fma_f32 v[96:97], v[96:97], v[182:183], v[100:101]
	v_lshlrev_b32_e32 v100, 16, v142
	v_and_b32_e32 v101, 0xffff0000, v142
	v_lshlrev_b32_e32 v102, 16, v143
	v_and_b32_e32 v103, 0xffff0000, v143
	v_pk_fma_f32 v[102:103], v[94:95], v[180:181], v[102:103]
	v_pk_fma_f32 v[94:95], v[92:93], v[178:179], v[100:101]
	v_cvt_pk_bf16_f32 v92, v96, v97
	v_lshl_add_u64 v[96:97], s[10:11], 0, v[192:193]
	v_cvt_pk_bf16_f32 v93, v98, v99
	v_cvt_pk_bf16_f32 v94, v94, v95
	v_cvt_pk_bf16_f32 v95, v102, v103
	v_lshl_add_u64 v[96:97], v[96:97], 0, v[186:187]
	global_store_dwordx4 v[96:97], v[92:95], off
	s_waitcnt vmcnt(7)
	s_nop 0
	v_lshlrev_b32_e32 v92, 16, v132
	v_and_b32_e32 v93, 0xffff0000, v132
	v_lshlrev_b32_e32 v94, 16, v133
	v_and_b32_e32 v95, 0xffff0000, v133
	v_pk_fma_f32 v[86:87], v[86:87], v[176:177], v[94:95]
	v_pk_fma_f32 v[84:85], v[84:85], v[174:175], v[92:93]
	v_lshlrev_b32_e32 v92, 16, v134
	v_and_b32_e32 v93, 0xffff0000, v134
	v_lshlrev_b32_e32 v94, 16, v135
	v_and_b32_e32 v95, 0xffff0000, v135
	v_pk_fma_f32 v[94:95], v[78:79], v[172:173], v[94:95]
	v_pk_fma_f32 v[78:79], v[76:77], v[170:171], v[92:93]
	v_cvt_pk_bf16_f32 v76, v84, v85
	v_cvt_pk_bf16_f32 v77, v86, v87
	s_waitcnt vmcnt(6)
	v_lshlrev_b32_e32 v84, 16, v146
	v_cvt_pk_bf16_f32 v78, v78, v79
	v_cvt_pk_bf16_f32 v79, v94, v95
	global_store_dwordx4 v[96:97], v[76:79], off offset:256
	v_and_b32_e32 v85, 0xffff0000, v146
	v_pk_fma_f32 v[80:81], v[80:81], v[178:179], v[84:85]
	v_lshlrev_b32_e32 v76, 16, v144
	v_and_b32_e32 v77, 0xffff0000, v144
	v_lshlrev_b32_e32 v78, 16, v145
	v_and_b32_e32 v79, 0xffff0000, v145
	v_pk_fma_f32 v[78:79], v[90:91], v[184:185], v[78:79]
	v_pk_fma_f32 v[76:77], v[88:89], v[182:183], v[76:77]
	v_lshlrev_b32_e32 v86, 16, v147
	v_and_b32_e32 v87, 0xffff0000, v147
	v_cvt_pk_bf16_f32 v76, v76, v77
	v_cvt_pk_bf16_f32 v77, v78, v79
	v_cvt_pk_bf16_f32 v78, v80, v81
	v_lshl_add_u64 v[80:81], s[10:11], 0, v[194:195]
	v_pk_fma_f32 v[82:83], v[82:83], v[180:181], v[86:87]
	v_lshl_add_u64 v[80:81], v[80:81], 0, v[186:187]
	v_cvt_pk_bf16_f32 v79, v82, v83
	global_store_dwordx4 v[80:81], v[76:79], off
	v_lshl_add_u64 v[84:85], v[190:191], 0, s[26:27]
	s_mov_b64 s[26:27], 0x90000
	s_waitcnt vmcnt(7)
	v_lshlrev_b32_e32 v76, 16, v136
	v_and_b32_e32 v77, 0xffff0000, v136
	v_lshlrev_b32_e32 v78, 16, v137
	v_and_b32_e32 v79, 0xffff0000, v137
	v_pk_fma_f32 v[74:75], v[74:75], v[176:177], v[78:79]
	v_pk_fma_f32 v[72:73], v[72:73], v[174:175], v[76:77]
	v_lshlrev_b32_e32 v76, 16, v138
	v_and_b32_e32 v77, 0xffff0000, v138
	v_lshlrev_b32_e32 v78, 16, v139
	v_and_b32_e32 v79, 0xffff0000, v139
	v_pk_fma_f32 v[78:79], v[70:71], v[172:173], v[78:79]
	v_pk_fma_f32 v[70:71], v[68:69], v[170:171], v[76:77]
	v_cvt_pk_bf16_f32 v68, v72, v73
	v_cvt_pk_bf16_f32 v69, v74, v75
	v_lshl_add_u64 v[88:89], v[190:191], 0, s[26:27]
	v_cvt_pk_bf16_f32 v70, v70, v71
	v_cvt_pk_bf16_f32 v71, v78, v79
	global_store_dwordx4 v[80:81], v[68:71], off offset:256
	s_mov_b64 s[26:27], 0xa0000
	v_lshl_add_u64 v[106:107], v[190:191], 0, s[26:27]
	v_lshl_add_u64 v[68:69], v[188:189], 0, v[84:85]
	v_mov_b64_e32 v[72:73], v[222:223]
	v_mov_b64_e32 v[74:75], v[224:225]
	v_mov_b64_e32 v[80:81], v[226:227]
	v_mov_b64_e32 v[82:83], v[228:229]
	v_lshl_add_u64 v[68:69], v[188:189], 0, v[88:89]
	v_mov_b64_e32 v[90:91], v[230:231]
	v_mov_b64_e32 v[92:93], v[232:233]
	v_mov_b64_e32 v[94:95], v[234:235]
	v_mov_b64_e32 v[96:97], v[236:237]
	v_lshl_add_u64 v[68:69], v[188:189], 0, v[106:107]
	v_mov_b64_e32 v[98:99], v[238:239]
	v_mov_b64_e32 v[100:101], v[240:241]
	v_mov_b64_e32 v[102:103], v[242:243]
	v_mov_b64_e32 v[104:105], v[244:245]
	s_mov_b64 s[26:27], 0xb0000
	v_lshl_add_u64 v[86:87], v[190:191], 0, s[26:27]
	v_lshl_add_u64 v[68:69], v[188:189], 0, v[86:87]
	v_mov_b64_e32 v[76:77], v[246:247]
	v_mov_b64_e32 v[78:79], v[248:249]
	s_nop 0
	v_mov_b64_e32 v[68:69], v[250:251]
	v_mov_b64_e32 v[70:71], v[252:253]
	s_mov_b64 s[26:27], -1
	s_waitcnt vmcnt(7)
	v_lshlrev_b32_e32 v108, 16, v72
	v_and_b32_e32 v109, 0xffff0000, v72
	v_lshlrev_b32_e32 v72, 16, v73
	v_and_b32_e32 v73, 0xffff0000, v73
	v_pk_fma_f32 v[66:67], v[66:67], v[184:185], v[72:73]
	v_pk_fma_f32 v[64:65], v[64:65], v[182:183], v[108:109]
	v_lshlrev_b32_e32 v72, 16, v74
	v_and_b32_e32 v73, 0xffff0000, v74
	v_lshlrev_b32_e32 v74, 16, v75
	v_and_b32_e32 v75, 0xffff0000, v75
	v_pk_fma_f32 v[74:75], v[62:63], v[180:181], v[74:75]
	v_pk_fma_f32 v[62:63], v[60:61], v[178:179], v[72:73]
	v_cvt_pk_bf16_f32 v60, v64, v65
	v_lshl_add_u64 v[64:65], s[10:11], 0, v[84:85]
	v_cvt_pk_bf16_f32 v61, v66, v67
	v_cvt_pk_bf16_f32 v62, v62, v63
	v_cvt_pk_bf16_f32 v63, v74, v75
	v_lshl_add_u64 v[64:65], v[64:65], 0, v[186:187]
	global_store_dwordx4 v[64:65], v[60:63], off
	s_waitcnt vmcnt(7)
	s_nop 0
	v_lshlrev_b32_e32 v60, 16, v80
	v_and_b32_e32 v61, 0xffff0000, v80
	v_lshlrev_b32_e32 v62, 16, v81
	v_and_b32_e32 v63, 0xffff0000, v81
	v_pk_fma_f32 v[58:59], v[58:59], v[176:177], v[62:63]
	v_pk_fma_f32 v[56:57], v[56:57], v[174:175], v[60:61]
	v_lshlrev_b32_e32 v60, 16, v82
	v_and_b32_e32 v61, 0xffff0000, v82
	v_lshlrev_b32_e32 v62, 16, v83
	v_and_b32_e32 v63, 0xffff0000, v83
	v_pk_fma_f32 v[62:63], v[54:55], v[172:173], v[62:63]
	v_pk_fma_f32 v[54:55], v[52:53], v[170:171], v[60:61]
	v_cvt_pk_bf16_f32 v52, v56, v57
	v_cvt_pk_bf16_f32 v53, v58, v59
	s_nop 0
	v_cvt_pk_bf16_f32 v54, v54, v55
	v_cvt_pk_bf16_f32 v55, v62, v63
	global_store_dwordx4 v[64:65], v[52:55], off offset:256
	s_waitcnt vmcnt(7)
	s_nop 0
	v_lshlrev_b32_e32 v52, 16, v90
	v_and_b32_e32 v53, 0xffff0000, v90
	v_lshlrev_b32_e32 v54, 16, v91
	v_and_b32_e32 v55, 0xffff0000, v91
	v_pk_fma_f32 v[50:51], v[50:51], v[184:185], v[54:55]
	v_pk_fma_f32 v[48:49], v[48:49], v[182:183], v[52:53]
	v_lshlrev_b32_e32 v52, 16, v92
	v_and_b32_e32 v53, 0xffff0000, v92
	v_lshlrev_b32_e32 v54, 16, v93
	v_and_b32_e32 v55, 0xffff0000, v93
	v_pk_fma_f32 v[54:55], v[46:47], v[180:181], v[54:55]
	v_pk_fma_f32 v[46:47], v[44:45], v[178:179], v[52:53]
	v_cvt_pk_bf16_f32 v44, v48, v49
	v_lshl_add_u64 v[48:49], s[10:11], 0, v[88:89]
	v_cvt_pk_bf16_f32 v45, v50, v51
	v_cvt_pk_bf16_f32 v46, v46, v47
	v_cvt_pk_bf16_f32 v47, v54, v55
	v_lshl_add_u64 v[48:49], v[48:49], 0, v[186:187]
	global_store_dwordx4 v[48:49], v[44:47], off
	s_waitcnt vmcnt(7)
	s_nop 0
	v_lshlrev_b32_e32 v44, 16, v94
	v_and_b32_e32 v45, 0xffff0000, v94
	v_lshlrev_b32_e32 v46, 16, v95
	v_and_b32_e32 v47, 0xffff0000, v95
	v_pk_fma_f32 v[42:43], v[42:43], v[176:177], v[46:47]
	v_pk_fma_f32 v[40:41], v[40:41], v[174:175], v[44:45]
	v_lshlrev_b32_e32 v44, 16, v96
	v_and_b32_e32 v45, 0xffff0000, v96
	v_lshlrev_b32_e32 v46, 16, v97
	v_and_b32_e32 v47, 0xffff0000, v97
	v_pk_fma_f32 v[46:47], v[38:39], v[172:173], v[46:47]
	v_pk_fma_f32 v[38:39], v[36:37], v[170:171], v[44:45]
	v_cvt_pk_bf16_f32 v36, v40, v41
	v_cvt_pk_bf16_f32 v37, v42, v43
	s_nop 0
	v_cvt_pk_bf16_f32 v38, v38, v39
	v_cvt_pk_bf16_f32 v39, v46, v47
	global_store_dwordx4 v[48:49], v[36:39], off offset:256
	s_waitcnt vmcnt(7)
	s_nop 0
	v_lshlrev_b32_e32 v36, 16, v98
	v_and_b32_e32 v37, 0xffff0000, v98
	v_lshlrev_b32_e32 v38, 16, v99
	v_and_b32_e32 v39, 0xffff0000, v99
	v_pk_fma_f32 v[34:35], v[34:35], v[184:185], v[38:39]
	v_pk_fma_f32 v[32:33], v[32:33], v[182:183], v[36:37]
	v_lshlrev_b32_e32 v36, 16, v100
	v_and_b32_e32 v37, 0xffff0000, v100
	v_lshlrev_b32_e32 v38, 16, v101
	v_and_b32_e32 v39, 0xffff0000, v101
	v_pk_fma_f32 v[38:39], v[30:31], v[180:181], v[38:39]
	v_pk_fma_f32 v[30:31], v[28:29], v[178:179], v[36:37]
	v_cvt_pk_bf16_f32 v28, v32, v33
	v_lshl_add_u64 v[32:33], s[10:11], 0, v[106:107]
	v_cvt_pk_bf16_f32 v29, v34, v35
	v_cvt_pk_bf16_f32 v30, v30, v31
	v_cvt_pk_bf16_f32 v31, v38, v39
	v_lshl_add_u64 v[32:33], v[32:33], 0, v[186:187]
	global_store_dwordx4 v[32:33], v[28:31], off
	s_waitcnt vmcnt(7)
	s_nop 0
	v_lshlrev_b32_e32 v28, 16, v102
	v_and_b32_e32 v29, 0xffff0000, v102
	v_lshlrev_b32_e32 v30, 16, v103
	v_and_b32_e32 v31, 0xffff0000, v103
	v_pk_fma_f32 v[26:27], v[26:27], v[176:177], v[30:31]
	v_pk_fma_f32 v[24:25], v[24:25], v[174:175], v[28:29]
	v_lshlrev_b32_e32 v28, 16, v104
	v_and_b32_e32 v29, 0xffff0000, v104
	v_lshlrev_b32_e32 v30, 16, v105
	v_and_b32_e32 v31, 0xffff0000, v105
	v_pk_fma_f32 v[30:31], v[22:23], v[172:173], v[30:31]
	v_pk_fma_f32 v[22:23], v[20:21], v[170:171], v[28:29]
	v_cvt_pk_bf16_f32 v20, v24, v25
	v_cvt_pk_bf16_f32 v21, v26, v27
	s_nop 0
	v_cvt_pk_bf16_f32 v22, v22, v23
	v_cvt_pk_bf16_f32 v23, v30, v31
	global_store_dwordx4 v[32:33], v[20:23], off offset:256
	s_waitcnt vmcnt(7)
	s_nop 0
	v_lshlrev_b32_e32 v20, 16, v76
	v_and_b32_e32 v21, 0xffff0000, v76
	v_lshlrev_b32_e32 v22, 16, v77
	v_and_b32_e32 v23, 0xffff0000, v77
	v_pk_fma_f32 v[18:19], v[18:19], v[184:185], v[22:23]
	v_pk_fma_f32 v[16:17], v[16:17], v[182:183], v[20:21]
	v_lshlrev_b32_e32 v20, 16, v78
	v_and_b32_e32 v21, 0xffff0000, v78
	v_lshlrev_b32_e32 v22, 16, v79
	v_and_b32_e32 v23, 0xffff0000, v79
	v_pk_fma_f32 v[22:23], v[14:15], v[180:181], v[22:23]
	v_pk_fma_f32 v[14:15], v[12:13], v[178:179], v[20:21]
	v_cvt_pk_bf16_f32 v12, v16, v17
	v_lshl_add_u64 v[16:17], s[10:11], 0, v[86:87]
	v_cvt_pk_bf16_f32 v13, v18, v19
	v_cvt_pk_bf16_f32 v14, v14, v15
	v_cvt_pk_bf16_f32 v15, v22, v23
	v_lshl_add_u64 v[16:17], v[16:17], 0, v[186:187]
	global_store_dwordx4 v[16:17], v[12:15], off
	s_waitcnt vmcnt(7)
	s_nop 0
	v_lshlrev_b32_e32 v12, 16, v68
	v_and_b32_e32 v13, 0xffff0000, v68
	v_lshlrev_b32_e32 v14, 16, v69
	v_and_b32_e32 v15, 0xffff0000, v69
	v_pk_fma_f32 v[10:11], v[10:11], v[176:177], v[14:15]
	v_pk_fma_f32 v[8:9], v[8:9], v[174:175], v[12:13]
	v_lshlrev_b32_e32 v12, 16, v70
	v_and_b32_e32 v13, 0xffff0000, v70
	v_lshlrev_b32_e32 v14, 16, v71
	v_and_b32_e32 v15, 0xffff0000, v71
	v_pk_fma_f32 v[14:15], v[6:7], v[172:173], v[14:15]
	v_pk_fma_f32 v[6:7], v[4:5], v[170:171], v[12:13]
	v_cvt_pk_bf16_f32 v4, v8, v9
	v_cvt_pk_bf16_f32 v5, v10, v11
	s_nop 0
	v_cvt_pk_bf16_f32 v6, v6, v7
	v_cvt_pk_bf16_f32 v7, v14, v15
	global_store_dwordx4 v[16:17], v[4:7], off offset:256
	s_cbranch_vccnz .LBB0_425
	s_andn2_b64 vcc, exec, s[8:9]
	s_cbranch_vccnz .LBB0_424
	s_barrier
	s_branch .LBB0_424

.LBB0_1216:
	v_lshl_or_b32 v148, s25, 8, v192
	v_lshl_add_u32 v150, s24, 8, v190
	s_lshl_b64 s[24:25], s[26:27], 2
	v_ashrrev_i32_e32 v149, 31, v148
	s_add_u32 s24, s77, s24
	v_lshlrev_b64 v[178:179], 1, v[148:149]
	v_ashrrev_i32_e32 v151, 31, v150
	s_addc_u32 s25, s78, s25
	v_lshl_add_u64 v[180:181], s[8:9], 0, v[178:179]
	v_lshlrev_b64 v[182:183], 12, v[150:151]
	v_lshl_add_u64 v[72:73], v[148:149], 2, s[24:25]
	v_lshl_add_u64 v[148:149], v[180:181], 0, v[182:183]
	s_mov_b64 vcc, 0x80000
	global_load_dwordx4 v[76:79], v[72:73], off offset:16
	global_load_dwordx4 v[80:83], v[72:73], off
	global_load_dwordx4 v[68:71], v[72:73], off offset:528
	s_nop 0
	global_load_dwordx4 v[72:75], v[72:73], off offset:512
	s_nop 0
	v_lshl_add_u64 v[212:213], v[148:149], 0, vcc
	global_load_dwordx4 v[222:225], v[212:213], off
	global_load_dwordx4 v[226:229], v[212:213], off offset:256
	global_load_dwordx4 v[200:203], v[148:149], off
	global_load_dwordx4 v[204:207], v[148:149], off offset:256
	v_or_b32_e32 v148, 16, v150
	v_ashrrev_i32_e32 v149, 31, v148
	v_lshlrev_b64 v[188:189], 12, v[148:149]
	v_lshl_add_u64 v[148:149], v[180:181], 0, v[188:189]
	v_lshl_add_u64 v[212:213], v[148:149], 0, vcc
	global_load_dwordx4 v[230:233], v[212:213], off
	global_load_dwordx4 v[234:237], v[212:213], off offset:256
	global_load_dwordx4 v[208:211], v[148:149], off
	global_load_dwordx4 v[164:167], v[148:149], off offset:256
	v_or_b32_e32 v148, 32, v150
	v_ashrrev_i32_e32 v149, 31, v148
	v_lshlrev_b64 v[186:187], 12, v[148:149]
	v_lshl_add_u64 v[148:149], v[180:181], 0, v[186:187]
	v_lshl_add_u64 v[212:213], v[148:149], 0, vcc
	global_load_dwordx4 v[238:241], v[212:213], off
	global_load_dwordx4 v[242:245], v[212:213], off offset:256
	global_load_dwordx4 v[160:163], v[148:149], off
	global_load_dwordx4 v[156:159], v[148:149], off offset:256
	v_or_b32_e32 v148, 48, v150
	v_ashrrev_i32_e32 v149, 31, v148
	v_lshlrev_b64 v[184:185], 12, v[148:149]
	v_lshl_add_u64 v[148:149], v[180:181], 0, v[184:185]
	v_lshl_add_u64 v[212:213], v[148:149], 0, vcc
	global_load_dwordx4 v[246:249], v[212:213], off
	global_load_dwordx4 v[250:253], v[212:213], off offset:256
	global_load_dwordx4 v[152:155], v[148:149], off
	s_nop 0
	global_load_dwordx4 v[148:151], v[148:149], off offset:256
	s_mov_b64 s[24:25], 0x80000
	s_andn2_b64 vcc, exec, s[4:5]
	s_waitcnt vmcnt(0)
	v_lshlrev_b32_e32 v194, 16, v200
	v_and_b32_e32 v195, 0xffff0000, v200
	v_lshlrev_b32_e32 v198, 16, v201
	v_and_b32_e32 v199, 0xffff0000, v201
	v_pk_fma_f32 v[146:147], v[146:147], v[82:83], v[198:199]
	v_pk_fma_f32 v[144:145], v[144:145], v[80:81], v[194:195]
	v_lshlrev_b32_e32 v194, 16, v202
	v_and_b32_e32 v195, 0xffff0000, v202
	v_lshlrev_b32_e32 v198, 16, v203
	v_and_b32_e32 v199, 0xffff0000, v203
	v_pk_fma_f32 v[198:199], v[142:143], v[78:79], v[198:199]
	v_pk_fma_f32 v[142:143], v[140:141], v[76:77], v[194:195]
	v_cvt_pk_bf16_f32 v140, v144, v145
	v_lshl_add_u64 v[144:145], s[8:9], 0, v[182:183]
	v_cvt_pk_bf16_f32 v141, v146, v147
	v_cvt_pk_bf16_f32 v142, v142, v143
	v_cvt_pk_bf16_f32 v143, v198, v199
	v_lshl_add_u64 v[144:145], v[144:145], 0, v[178:179]
	global_store_dwordx4 v[144:145], v[140:143], off
	s_nop 1
	v_lshlrev_b32_e32 v140, 16, v204
	v_and_b32_e32 v141, 0xffff0000, v204
	v_lshlrev_b32_e32 v142, 16, v205
	v_and_b32_e32 v143, 0xffff0000, v205
	v_pk_fma_f32 v[134:135], v[134:135], v[74:75], v[142:143]
	v_pk_fma_f32 v[132:133], v[132:133], v[72:73], v[140:141]
	v_lshlrev_b32_e32 v140, 16, v206
	v_and_b32_e32 v141, 0xffff0000, v206
	v_lshlrev_b32_e32 v142, 16, v207
	v_and_b32_e32 v143, 0xffff0000, v207
	v_pk_fma_f32 v[142:143], v[126:127], v[70:71], v[142:143]
	v_pk_fma_f32 v[126:127], v[124:125], v[68:69], v[140:141]
	v_cvt_pk_bf16_f32 v124, v132, v133
	v_cvt_pk_bf16_f32 v125, v134, v135
	v_lshlrev_b32_e32 v132, 16, v210
	v_cvt_pk_bf16_f32 v126, v126, v127
	v_cvt_pk_bf16_f32 v127, v142, v143
	global_store_dwordx4 v[144:145], v[124:127], off offset:256
	v_and_b32_e32 v133, 0xffff0000, v210
	v_pk_fma_f32 v[128:129], v[128:129], v[76:77], v[132:133]
	v_lshlrev_b32_e32 v124, 16, v208
	v_and_b32_e32 v125, 0xffff0000, v208
	v_lshlrev_b32_e32 v126, 16, v209
	v_and_b32_e32 v127, 0xffff0000, v209
	v_pk_fma_f32 v[126:127], v[138:139], v[82:83], v[126:127]
	v_pk_fma_f32 v[124:125], v[136:137], v[80:81], v[124:125]
	v_lshlrev_b32_e32 v134, 16, v211
	v_and_b32_e32 v135, 0xffff0000, v211
	v_cvt_pk_bf16_f32 v124, v124, v125
	v_cvt_pk_bf16_f32 v125, v126, v127
	v_cvt_pk_bf16_f32 v126, v128, v129
	v_lshl_add_u64 v[128:129], s[8:9], 0, v[188:189]
	v_pk_fma_f32 v[130:131], v[130:131], v[78:79], v[134:135]
	v_lshl_add_u64 v[128:129], v[128:129], 0, v[178:179]
	v_cvt_pk_bf16_f32 v127, v130, v131
	global_store_dwordx4 v[128:129], v[124:127], off
	s_nop 1
	v_lshlrev_b32_e32 v124, 16, v164
	v_and_b32_e32 v125, 0xffff0000, v164
	v_lshlrev_b32_e32 v126, 16, v165
	v_and_b32_e32 v127, 0xffff0000, v165
	v_pk_fma_f32 v[122:123], v[122:123], v[74:75], v[126:127]
	v_pk_fma_f32 v[120:121], v[120:121], v[72:73], v[124:125]
	v_lshlrev_b32_e32 v124, 16, v166
	v_and_b32_e32 v125, 0xffff0000, v166
	v_lshlrev_b32_e32 v126, 16, v167
	v_and_b32_e32 v127, 0xffff0000, v167
	v_pk_fma_f32 v[126:127], v[118:119], v[70:71], v[126:127]
	v_pk_fma_f32 v[118:119], v[116:117], v[68:69], v[124:125]
	v_cvt_pk_bf16_f32 v116, v120, v121
	v_cvt_pk_bf16_f32 v117, v122, v123
	s_nop 0
	v_cvt_pk_bf16_f32 v118, v118, v119
	v_cvt_pk_bf16_f32 v119, v126, v127
	global_store_dwordx4 v[128:129], v[116:119], off offset:256
	s_nop 1
	v_lshlrev_b32_e32 v116, 16, v160
	v_and_b32_e32 v117, 0xffff0000, v160
	v_lshlrev_b32_e32 v118, 16, v161
	v_and_b32_e32 v119, 0xffff0000, v161
	v_pk_fma_f32 v[114:115], v[114:115], v[82:83], v[118:119]
	v_pk_fma_f32 v[112:113], v[112:113], v[80:81], v[116:117]
	v_lshlrev_b32_e32 v116, 16, v162
	v_and_b32_e32 v117, 0xffff0000, v162
	v_lshlrev_b32_e32 v118, 16, v163
	v_and_b32_e32 v119, 0xffff0000, v163
	v_pk_fma_f32 v[118:119], v[110:111], v[78:79], v[118:119]
	v_pk_fma_f32 v[110:111], v[108:109], v[76:77], v[116:117]
	v_cvt_pk_bf16_f32 v108, v112, v113
	v_lshl_add_u64 v[112:113], s[8:9], 0, v[186:187]
	v_cvt_pk_bf16_f32 v109, v114, v115
	v_cvt_pk_bf16_f32 v110, v110, v111
	v_cvt_pk_bf16_f32 v111, v118, v119
	v_lshl_add_u64 v[112:113], v[112:113], 0, v[178:179]
	global_store_dwordx4 v[112:113], v[108:111], off
	s_nop 1
	v_lshlrev_b32_e32 v108, 16, v156
	v_and_b32_e32 v109, 0xffff0000, v156
	v_lshlrev_b32_e32 v110, 16, v157
	v_and_b32_e32 v111, 0xffff0000, v157
	v_pk_fma_f32 v[102:103], v[102:103], v[74:75], v[110:111]
	v_pk_fma_f32 v[100:101], v[100:101], v[72:73], v[108:109]
	v_lshlrev_b32_e32 v108, 16, v158
	v_and_b32_e32 v109, 0xffff0000, v158
	v_lshlrev_b32_e32 v110, 16, v159
	v_and_b32_e32 v111, 0xffff0000, v159
	v_pk_fma_f32 v[110:111], v[94:95], v[70:71], v[110:111]
	v_pk_fma_f32 v[94:95], v[92:93], v[68:69], v[108:109]
	v_cvt_pk_bf16_f32 v92, v100, v101
	v_cvt_pk_bf16_f32 v93, v102, v103
	v_lshlrev_b32_e32 v100, 16, v154
	v_cvt_pk_bf16_f32 v94, v94, v95
	v_cvt_pk_bf16_f32 v95, v110, v111
	global_store_dwordx4 v[112:113], v[92:95], off offset:256
	v_and_b32_e32 v101, 0xffff0000, v154
	v_pk_fma_f32 v[96:97], v[96:97], v[76:77], v[100:101]
	v_lshlrev_b32_e32 v92, 16, v152
	v_and_b32_e32 v93, 0xffff0000, v152
	v_lshlrev_b32_e32 v94, 16, v153
	v_and_b32_e32 v95, 0xffff0000, v153
	v_pk_fma_f32 v[94:95], v[106:107], v[82:83], v[94:95]
	v_pk_fma_f32 v[92:93], v[104:105], v[80:81], v[92:93]
	v_lshlrev_b32_e32 v102, 16, v155
	v_and_b32_e32 v103, 0xffff0000, v155
	v_cvt_pk_bf16_f32 v92, v92, v93
	v_cvt_pk_bf16_f32 v93, v94, v95
	v_cvt_pk_bf16_f32 v94, v96, v97
	v_lshl_add_u64 v[96:97], s[8:9], 0, v[184:185]
	v_pk_fma_f32 v[98:99], v[98:99], v[78:79], v[102:103]
	v_lshl_add_u64 v[96:97], v[96:97], 0, v[178:179]
	v_cvt_pk_bf16_f32 v95, v98, v99
	global_store_dwordx4 v[96:97], v[92:95], off
	v_lshl_add_u64 v[100:101], v[182:183], 0, s[24:25]
	s_mov_b64 s[24:25], 0x90000
	v_lshlrev_b32_e32 v92, 16, v148
	v_and_b32_e32 v93, 0xffff0000, v148
	v_lshlrev_b32_e32 v94, 16, v149
	v_and_b32_e32 v95, 0xffff0000, v149
	v_pk_fma_f32 v[90:91], v[90:91], v[74:75], v[94:95]
	v_pk_fma_f32 v[88:89], v[88:89], v[72:73], v[92:93]
	v_lshlrev_b32_e32 v92, 16, v150
	v_and_b32_e32 v93, 0xffff0000, v150
	v_lshlrev_b32_e32 v94, 16, v151
	v_and_b32_e32 v95, 0xffff0000, v151
	v_pk_fma_f32 v[94:95], v[86:87], v[70:71], v[94:95]
	v_pk_fma_f32 v[86:87], v[84:85], v[68:69], v[92:93]
	v_cvt_pk_bf16_f32 v84, v88, v89
	v_cvt_pk_bf16_f32 v85, v90, v91
	v_lshl_add_u64 v[104:105], v[182:183], 0, s[24:25]
	v_cvt_pk_bf16_f32 v86, v86, v87
	v_cvt_pk_bf16_f32 v87, v94, v95
	global_store_dwordx4 v[96:97], v[84:87], off offset:256
	s_mov_b64 s[24:25], 0xa0000
	v_lshl_add_u64 v[122:123], v[182:183], 0, s[24:25]
	v_lshl_add_u64 v[84:85], v[180:181], 0, v[100:101]
	v_mov_b64_e32 v[88:89], v[222:223]
	v_mov_b64_e32 v[90:91], v[224:225]
	v_mov_b64_e32 v[96:97], v[226:227]
	v_mov_b64_e32 v[98:99], v[228:229]
	v_lshl_add_u64 v[84:85], v[180:181], 0, v[104:105]
	v_mov_b64_e32 v[106:107], v[230:231]
	v_mov_b64_e32 v[108:109], v[232:233]
	v_mov_b64_e32 v[110:111], v[234:235]
	v_mov_b64_e32 v[112:113], v[236:237]
	v_lshl_add_u64 v[84:85], v[180:181], 0, v[122:123]
	v_mov_b64_e32 v[114:115], v[238:239]
	v_mov_b64_e32 v[116:117], v[240:241]
	v_mov_b64_e32 v[118:119], v[242:243]
	v_mov_b64_e32 v[120:121], v[244:245]
	s_mov_b64 s[24:25], 0xb0000
	v_lshl_add_u64 v[102:103], v[182:183], 0, s[24:25]
	v_lshl_add_u64 v[84:85], v[180:181], 0, v[102:103]
	v_mov_b64_e32 v[92:93], v[246:247]
	v_mov_b64_e32 v[94:95], v[248:249]
	s_nop 0
	v_mov_b64_e32 v[84:85], v[250:251]
	v_mov_b64_e32 v[86:87], v[252:253]
	s_mov_b64 s[24:25], -1
	s_waitcnt vmcnt(7)
	v_lshlrev_b32_e32 v124, 16, v88
	v_and_b32_e32 v125, 0xffff0000, v88
	v_lshlrev_b32_e32 v88, 16, v89
	v_and_b32_e32 v89, 0xffff0000, v89
	v_pk_fma_f32 v[66:67], v[66:67], v[82:83], v[88:89]
	v_pk_fma_f32 v[64:65], v[64:65], v[80:81], v[124:125]
	v_lshlrev_b32_e32 v88, 16, v90
	v_and_b32_e32 v89, 0xffff0000, v90
	v_lshlrev_b32_e32 v90, 16, v91
	v_and_b32_e32 v91, 0xffff0000, v91
	v_pk_fma_f32 v[90:91], v[62:63], v[78:79], v[90:91]
	v_pk_fma_f32 v[62:63], v[60:61], v[76:77], v[88:89]
	v_cvt_pk_bf16_f32 v60, v64, v65
	v_lshl_add_u64 v[64:65], s[8:9], 0, v[100:101]
	v_cvt_pk_bf16_f32 v61, v66, v67
	v_cvt_pk_bf16_f32 v62, v62, v63
	v_cvt_pk_bf16_f32 v63, v90, v91
	v_lshl_add_u64 v[64:65], v[64:65], 0, v[178:179]
	global_store_dwordx4 v[64:65], v[60:63], off
	s_waitcnt vmcnt(7)
	s_nop 0
	v_lshlrev_b32_e32 v60, 16, v96
	v_and_b32_e32 v61, 0xffff0000, v96
	v_lshlrev_b32_e32 v62, 16, v97
	v_and_b32_e32 v63, 0xffff0000, v97
	v_pk_fma_f32 v[58:59], v[58:59], v[74:75], v[62:63]
	v_pk_fma_f32 v[56:57], v[56:57], v[72:73], v[60:61]
	v_lshlrev_b32_e32 v60, 16, v98
	v_and_b32_e32 v61, 0xffff0000, v98
	v_lshlrev_b32_e32 v62, 16, v99
	v_and_b32_e32 v63, 0xffff0000, v99
	v_pk_fma_f32 v[62:63], v[54:55], v[70:71], v[62:63]
	v_pk_fma_f32 v[54:55], v[52:53], v[68:69], v[60:61]
	v_cvt_pk_bf16_f32 v52, v56, v57
	v_cvt_pk_bf16_f32 v53, v58, v59
	s_nop 0
	v_cvt_pk_bf16_f32 v54, v54, v55
	v_cvt_pk_bf16_f32 v55, v62, v63
	global_store_dwordx4 v[64:65], v[52:55], off offset:256
	s_waitcnt vmcnt(7)
	s_nop 0
	v_lshlrev_b32_e32 v52, 16, v106
	v_and_b32_e32 v53, 0xffff0000, v106
	v_lshlrev_b32_e32 v54, 16, v107
	v_and_b32_e32 v55, 0xffff0000, v107
	v_pk_fma_f32 v[50:51], v[50:51], v[82:83], v[54:55]
	v_pk_fma_f32 v[48:49], v[48:49], v[80:81], v[52:53]
	v_lshlrev_b32_e32 v52, 16, v108
	v_and_b32_e32 v53, 0xffff0000, v108
	v_lshlrev_b32_e32 v54, 16, v109
	v_and_b32_e32 v55, 0xffff0000, v109
	v_pk_fma_f32 v[54:55], v[46:47], v[78:79], v[54:55]
	v_pk_fma_f32 v[46:47], v[44:45], v[76:77], v[52:53]
	v_cvt_pk_bf16_f32 v44, v48, v49
	v_lshl_add_u64 v[48:49], s[8:9], 0, v[104:105]
	v_cvt_pk_bf16_f32 v45, v50, v51
	v_cvt_pk_bf16_f32 v46, v46, v47
	v_cvt_pk_bf16_f32 v47, v54, v55
	v_lshl_add_u64 v[48:49], v[48:49], 0, v[178:179]
	global_store_dwordx4 v[48:49], v[44:47], off
	s_waitcnt vmcnt(7)
	s_nop 0
	v_lshlrev_b32_e32 v44, 16, v110
	v_and_b32_e32 v45, 0xffff0000, v110
	v_lshlrev_b32_e32 v46, 16, v111
	v_and_b32_e32 v47, 0xffff0000, v111
	v_pk_fma_f32 v[42:43], v[42:43], v[74:75], v[46:47]
	v_pk_fma_f32 v[40:41], v[40:41], v[72:73], v[44:45]
	v_lshlrev_b32_e32 v44, 16, v112
	v_and_b32_e32 v45, 0xffff0000, v112
	v_lshlrev_b32_e32 v46, 16, v113
	v_and_b32_e32 v47, 0xffff0000, v113
	v_pk_fma_f32 v[46:47], v[38:39], v[70:71], v[46:47]
	v_pk_fma_f32 v[38:39], v[36:37], v[68:69], v[44:45]
	v_cvt_pk_bf16_f32 v36, v40, v41
	v_cvt_pk_bf16_f32 v37, v42, v43
	s_nop 0
	v_cvt_pk_bf16_f32 v38, v38, v39
	v_cvt_pk_bf16_f32 v39, v46, v47
	global_store_dwordx4 v[48:49], v[36:39], off offset:256
	s_waitcnt vmcnt(7)
	s_nop 0
	v_lshlrev_b32_e32 v36, 16, v114
	v_and_b32_e32 v37, 0xffff0000, v114
	v_lshlrev_b32_e32 v38, 16, v115
	v_and_b32_e32 v39, 0xffff0000, v115
	v_pk_fma_f32 v[34:35], v[34:35], v[82:83], v[38:39]
	v_pk_fma_f32 v[32:33], v[32:33], v[80:81], v[36:37]
	v_lshlrev_b32_e32 v36, 16, v116
	v_and_b32_e32 v37, 0xffff0000, v116
	v_lshlrev_b32_e32 v38, 16, v117
	v_and_b32_e32 v39, 0xffff0000, v117
	v_pk_fma_f32 v[38:39], v[30:31], v[78:79], v[38:39]
	v_pk_fma_f32 v[30:31], v[28:29], v[76:77], v[36:37]
	v_cvt_pk_bf16_f32 v28, v32, v33
	v_lshl_add_u64 v[32:33], s[8:9], 0, v[122:123]
	v_cvt_pk_bf16_f32 v29, v34, v35
	v_cvt_pk_bf16_f32 v30, v30, v31
	v_cvt_pk_bf16_f32 v31, v38, v39
	v_lshl_add_u64 v[32:33], v[32:33], 0, v[178:179]
	global_store_dwordx4 v[32:33], v[28:31], off
	s_waitcnt vmcnt(7)
	s_nop 0
	v_lshlrev_b32_e32 v28, 16, v118
	v_and_b32_e32 v29, 0xffff0000, v118
	v_lshlrev_b32_e32 v30, 16, v119
	v_and_b32_e32 v31, 0xffff0000, v119
	v_pk_fma_f32 v[26:27], v[26:27], v[74:75], v[30:31]
	v_pk_fma_f32 v[24:25], v[24:25], v[72:73], v[28:29]
	v_lshlrev_b32_e32 v28, 16, v120
	v_and_b32_e32 v29, 0xffff0000, v120
	v_lshlrev_b32_e32 v30, 16, v121
	v_and_b32_e32 v31, 0xffff0000, v121
	v_pk_fma_f32 v[30:31], v[22:23], v[70:71], v[30:31]
	v_pk_fma_f32 v[22:23], v[20:21], v[68:69], v[28:29]
	v_cvt_pk_bf16_f32 v20, v24, v25
	v_cvt_pk_bf16_f32 v21, v26, v27
	s_nop 0
	v_cvt_pk_bf16_f32 v22, v22, v23
	v_cvt_pk_bf16_f32 v23, v30, v31
	global_store_dwordx4 v[32:33], v[20:23], off offset:256
	s_waitcnt vmcnt(7)
	s_nop 0
	v_lshlrev_b32_e32 v20, 16, v92
	v_and_b32_e32 v21, 0xffff0000, v92
	v_lshlrev_b32_e32 v22, 16, v93
	v_and_b32_e32 v23, 0xffff0000, v93
	v_pk_fma_f32 v[18:19], v[18:19], v[82:83], v[22:23]
	v_pk_fma_f32 v[16:17], v[16:17], v[80:81], v[20:21]
	v_lshlrev_b32_e32 v20, 16, v94
	v_and_b32_e32 v21, 0xffff0000, v94
	v_lshlrev_b32_e32 v22, 16, v95
	v_and_b32_e32 v23, 0xffff0000, v95
	v_pk_fma_f32 v[22:23], v[14:15], v[78:79], v[22:23]
	v_pk_fma_f32 v[14:15], v[12:13], v[76:77], v[20:21]
	v_cvt_pk_bf16_f32 v12, v16, v17
	v_lshl_add_u64 v[16:17], s[8:9], 0, v[102:103]
	v_cvt_pk_bf16_f32 v13, v18, v19
	v_cvt_pk_bf16_f32 v14, v14, v15
	v_cvt_pk_bf16_f32 v15, v22, v23
	v_lshl_add_u64 v[16:17], v[16:17], 0, v[178:179]
	global_store_dwordx4 v[16:17], v[12:15], off
	s_waitcnt vmcnt(7)
	s_nop 0
	v_lshlrev_b32_e32 v12, 16, v84
	v_and_b32_e32 v13, 0xffff0000, v84
	v_lshlrev_b32_e32 v14, 16, v85
	v_and_b32_e32 v15, 0xffff0000, v85
	v_pk_fma_f32 v[10:11], v[10:11], v[74:75], v[14:15]
	v_pk_fma_f32 v[8:9], v[8:9], v[72:73], v[12:13]
	v_lshlrev_b32_e32 v12, 16, v86
	v_and_b32_e32 v13, 0xffff0000, v86
	v_lshlrev_b32_e32 v14, 16, v87
	v_and_b32_e32 v15, 0xffff0000, v87
	v_pk_fma_f32 v[14:15], v[6:7], v[70:71], v[14:15]
	v_pk_fma_f32 v[6:7], v[4:5], v[68:69], v[12:13]
	v_cvt_pk_bf16_f32 v4, v8, v9
	v_cvt_pk_bf16_f32 v5, v10, v11
	s_nop 0
	v_cvt_pk_bf16_f32 v6, v6, v7
	v_cvt_pk_bf16_f32 v7, v14, v15
	global_store_dwordx4 v[16:17], v[4:7], off offset:256
	s_cbranch_vccnz .LBB0_1203
	s_andn2_b64 vcc, exec, s[6:7]
	s_cbranch_vccnz .LBB0_1202
	s_barrier
	s_branch .LBB0_1202
